# v47: P6 masked intra-chunk score block: operand reads of steps j+1,j+2 in flight during step j (uses the idle oT accumulator registers as extra operand buffers)
# baseline (speedup 1.0000x reference)
; #define LAS __attribute__((address_space(3)))
; __device__ __forceinline__ unsigned short f2bf(float f) { return (unsigned short)(cvtpk(f, 0.f) & 0xffffu); }
; template <class T> __device__ __forceinline__ LAS T* opq(LAS T* p) { unsigned a = __builtin_bit_cast(unsigned, p); asm volatile("" : "+v"(a)); return __builtin_bit_cast(LAS T*, a); }
; #define MFMA32(a, b, c) __builtin_amdgcn_mfma_f32_32x32x16_bf16((a), (b), (c), 0, 0, 0)
; template <bool FULL, bool PARTIAL  > ...
;     ...
;             if (w < 3) {
;                 const int tb = w == 0 ? 0 : 1, sb = w == 2 ? 1 : 0;
;                 const LAS bf16_t* qa_r = opq(QS + (32 * tb + r) * QST + 8 * h); const LAS bf16_t* kb_r = opq(KS + (32 * sb + r) * QST + 8 * h);
;                 f32x16 a = {0.f, 0.f, 0.f, 0.f, 0.f, 0.f, 0.f, 0.f, 0.f, 0.f, 0.f, 0.f, 0.f, 0.f, 0.f, 0.f};
; #pragma unroll
;                 for (int s = 0; s < 8; ++s) {
;                     const bf16x8 qa = *(const LAS bf16x8*)(qa_r + 16 * s);
;                     const bf16x8 kb2 = *(const LAS bf16x8*)(kb_r + 16 * s);
;                     a = MFMA32(qa, kb2, a);
;                 }
;                 LAS bf16_t* ab_w = opq(Ab + (32 * tb + 4 * h) * TST + 32 * sb + r);
;                 const int dl = 32 * sb + r - 32 * tb - 4 * h;
; #pragma unroll
;                 for (int i = 0; i < 16; ++i) ab_w[((i & 3) + 8 * (i >> 2)) * TST] = f2bf(dl <= (i & 3) + 8 * (i >> 2) ? a[i] : 0.f);
;             }
.LBB0_1322:
	s_andn2_b64 vcc, exec, s[84:85]
	s_waitcnt lgkmcnt(0)
	s_barrier
	s_cbranch_vccnz .LBB0_1324
	v_mov_b32_e32 v2, v242
	v_mov_b32_e32 v12, v243
	ds_read_b128 v[4:7], v2
	ds_read_b128 v[8:11], v12
	ds_read_b128 v[114:117], v2 offset:32
	ds_read_b128 v[118:121], v12 offset:32
	ds_read_b128 v[122:125], v2 offset:64
	ds_read_b128 v[126:129], v12 offset:64
	s_waitcnt lgkmcnt(4)
	v_mfma_f32_32x32x16_bf16 v[98:113], v[4:7], v[8:11], 0
	ds_read_b128 v[4:7], v2 offset:96
	ds_read_b128 v[8:11], v12 offset:96
	s_waitcnt lgkmcnt(4)
	v_mfma_f32_32x32x16_bf16 v[98:113], v[114:117], v[118:121], v[98:113]
	ds_read_b128 v[114:117], v2 offset:128
	ds_read_b128 v[118:121], v12 offset:128
	s_waitcnt lgkmcnt(4)
	v_mfma_f32_32x32x16_bf16 v[98:113], v[122:125], v[126:129], v[98:113]
	ds_read_b128 v[122:125], v2 offset:160
	ds_read_b128 v[126:129], v12 offset:160
	s_waitcnt lgkmcnt(4)
	v_mfma_f32_32x32x16_bf16 v[98:113], v[4:7], v[8:11], v[98:113]
	ds_read_b128 v[4:7], v2 offset:192
	ds_read_b128 v[8:11], v12 offset:192
	s_waitcnt lgkmcnt(4)
	v_mfma_f32_32x32x16_bf16 v[98:113], v[114:117], v[118:121], v[98:113]
	ds_read_b128 v[114:117], v2 offset:224
	ds_read_b128 v[118:121], v12 offset:224
	s_waitcnt lgkmcnt(4)
	v_mfma_f32_32x32x16_bf16 v[98:113], v[122:125], v[126:129], v[98:113]
	s_waitcnt lgkmcnt(2)
	v_mfma_f32_32x32x16_bf16 v[98:113], v[4:7], v[8:11], v[98:113]
	v_mov_b32_e32 v2, v244
	s_waitcnt lgkmcnt(0)
	v_mfma_f32_32x32x16_bf16 v[98:113], v[114:117], v[118:121], v[98:113]
	s_nop 11
	v_cvt_pk_bf16_f32 v4, v98, s0
	v_cvt_pk_bf16_f32 v5, v99, s0
	v_cvt_pk_bf16_f32 v6, v100, s0
	v_cvt_pk_bf16_f32 v7, v101, s0
	v_cvt_pk_bf16_f32 v8, v102, s0
	v_cvt_pk_bf16_f32 v9, v103, s0
	v_cvt_pk_bf16_f32 v10, v104, s0
	v_cvt_pk_bf16_f32 v11, v105, s0
	v_cvt_pk_bf16_f32 v12, v106, s0
	v_cvt_pk_bf16_f32 v13, v107, s0
	v_cvt_pk_bf16_f32 v14, v108, s0
	v_cvt_pk_bf16_f32 v15, v109, s0
	v_cvt_pk_bf16_f32 v98, v110, s0
	v_cvt_pk_bf16_f32 v99, v111, s0
	v_cvt_pk_bf16_f32 v100, v112, s0
	v_cvt_pk_bf16_f32 v101, v113, s0
	v_cndmask_b32_e64 v4, v4, 0, s[6:7]
	v_cndmask_b32_e64 v5, v5, 0, s[8:9]
	v_cndmask_b32_e64 v6, v6, 0, s[10:11]
	v_cndmask_b32_e64 v7, v7, 0, s[12:13]
	v_cndmask_b32_e64 v8, v8, 0, s[14:15]
	v_cndmask_b32_e64 v9, v9, 0, s[16:17]
	v_cndmask_b32_e64 v10, v10, 0, s[18:19]
	v_cndmask_b32_e64 v11, v11, 0, s[20:21]
	v_cndmask_b32_e64 v12, v12, 0, s[22:23]
	v_cndmask_b32_e64 v13, v13, 0, s[24:25]
	v_cndmask_b32_e64 v14, v14, 0, s[26:27]
	v_cndmask_b32_e64 v15, v15, 0, s[28:29]
	v_cndmask_b32_e64 v98, v98, 0, s[30:31]
	v_cndmask_b32_e64 v99, v99, 0, s[34:35]
	v_cndmask_b32_e64 v100, v100, 0, s[36:37]
	v_cndmask_b32_e64 v101, v101, 0, s[38:39]
	ds_write_b16 v2, v4
	ds_write_b16 v2, v5 offset:144
	ds_write_b16 v2, v6 offset:288
	ds_write_b16 v2, v7 offset:432
	ds_write_b16 v2, v8 offset:1152
	ds_write_b16 v2, v9 offset:1296
	ds_write_b16 v2, v10 offset:1440
	ds_write_b16 v2, v11 offset:1584
	ds_write_b16 v2, v12 offset:2304
	ds_write_b16 v2, v13 offset:2448
	ds_write_b16 v2, v14 offset:2592
	ds_write_b16 v2, v15 offset:2736
	ds_write_b16 v2, v98 offset:3456
	ds_write_b16 v2, v99 offset:3600
	ds_write_b16 v2, v100 offset:3744
	ds_write_b16 v2, v101 offset:3888
